# prologue->projection grid barrier rewritten: arrival ticket and XCC population words fetched in one round trip, no generation hop, L1 invalidate before the wait
# baseline (speedup 1.0000x reference)
; __device__ __forceinline__ unsigned xb_ld(unsigned* p)              { return __hip_atomic_load(p, __ATOMIC_RELAXED, __HIP_MEMORY_SCOPE_AGENT); }
; __device__ __forceinline__ unsigned xb_add(unsigned* p, unsigned v) { return __hip_atomic_fetch_add(p, v, __ATOMIC_RELAXED, __HIP_MEMORY_SCOPE_AGENT); }
; #define XB_SPIN(cond, bar) do { unsigned _sp = 0; while (cond) { __builtin_amdgcn_s_sleep(1); \
;     if ((++_sp & 255u) == 0u) { if (xb_ld(&(bar)[XB_TMO])) break; if (_sp > XB_SPIN_CAP) { atomicAdd(&(bar)[XB_TMO], 1u); break; } } } } while (0)
; __device__ __forceinline__ void xcd_barrier_complete(unsigned* bar, unsigned x, unsigned& nloc, unsigned& nx) {
;     const unsigned G = gridDim.x * gridDim.y * gridDim.z;
;     unsigned sum, cnt, mine, sp = 0u;
;     for (;;) {
;         sum = 0u; cnt = 0u; mine = 0u;
; #pragma unroll
;         for (unsigned j = 0; j < 16; ++j) { const unsigned c = xb_ld(&bar[XB_XCNT(j)]); sum += c; cnt += (c > 0u) ? 1u : 0u; mine = (j == x) ? c : mine; }
;         if (sum == G) break;
;         __builtin_amdgcn_s_sleep(1);
;         if ((++sp & 255u) == 0u) { if (xb_ld(&bar[XB_TMO])) break; if (sp > XB_SPIN_CAP) { atomicAdd(&bar[XB_TMO], 1u); break; } }
;     }
;     nloc = mine > 0u ? mine : 1u; nx = cnt > 0u ? cnt : 1u;
; }
; __device__ __forceinline__ void xcd_barrier(const XcdBarrier& b) {
;     asm volatile("s_waitcnt vmcnt(0)" ::: "memory");
;     __syncthreads();
;     if (threadIdx.x == 0) {
;         unsigned* bar = b.bar;
;         __builtin_amdgcn_s_waitcnt(0);
;         unsigned nloc = b.st[0], nx = b.st[1];
;         if (nloc == 0u) { xcd_barrier_complete(bar, b.x, nloc, nx); b.st[0] = nloc; b.st[1] = nx; }
;         const unsigned old = xb_add(&bar[XB_XSUB(b.x)], 1u);
;         const unsigned gen = old / nloc;
;         if (old + 1u == (gen + 1u) * nloc) {
;             __builtin_amdgcn_fence(__ATOMIC_RELEASE, "agent");
;             asm volatile("s_waitcnt vmcnt(0)" ::: "memory");
;             const unsigned og = xb_add(&bar[XB_TOP], 1u);
;             const unsigned tg = og / nx;
;             if (og + 1u == (tg + 1u) * nx) xb_add(&bar[XB_TOPGEN], 1u);
;             else XB_SPIN(xb_ld(&bar[XB_TOPGEN]) == tg, bar);
.LBB0_101:
	s_cmp_lt_i32 s19, 2
	s_cbranch_scc1 .LBB0_155
	s_waitcnt vmcnt(0)
	s_waitcnt lgkmcnt(0)
	s_barrier
	s_mov_b64 s[0:1], exec
	v_readlane_b32 s2, v247, 37
	v_readlane_b32 s3, v247, 38
	s_and_b64 s[2:3], s[0:1], s[2:3]
	s_mov_b64 exec, s[2:3]
	s_cbranch_execz .LBB0_154
	v_readlane_b32 s4, v247, 36
	s_nop 0
	s_and_b32 s2, s4, 7
	s_lshl_b32 s2, s2, 2
	s_cmp_gt_u32 s4, 7
	s_cselect_b32 s3, 7, 1
	s_lshl_b32 s3, s3, s2
	v_mov_b32_e32 v2, s3
	s_and_b32 s2, s90, 31
	s_lshl_b32 s2, s2, 6
	s_add_u32 s2, s62, s2
	s_addc_u32 s3, s63, 0
	s_add_u32 s2, s2, 0xa000
	s_addc_u32 s3, s3, 0
	v_mov_b32_e32 v1, 0
	global_atomic_add v1, v2, s[2:3]
	s_and_b32 s2, s4, 3
	s_lshl_b32 s2, s2, 3
	s_cmp_gt_u32 s4, 7
	s_cselect_b32 s3, 33, 1
	s_lshl_b32 s3, s3, s2
	v_mov_b32_e32 v2, s3
	s_and_b32 s2, s90, 7
	s_lshl_b32 s2, s2, 7
	s_lshr_b32 s3, s4, 2
	s_and_b32 s3, s3, 1
	s_lshl_b32 s3, s3, 6
	s_add_i32 s2, s2, s3
	s_add_u32 s2, s62, s2
	s_addc_u32 s3, s63, 0
	s_add_u32 s2, s2, 0xa800
	s_addc_u32 s3, s3, 0
	global_atomic_add v1, v2, s[2:3]
	v_readlane_b32 s4, v247, 36
	s_add_u32 s2, s62, 0x4400
	s_addc_u32 s3, s63, 0
	s_lshl_b32 s5, s4, 8
	s_add_u32 s6, s2, s5
	s_addc_u32 s7, s3, 0
	s_add_u32 s8, s6, 0x1000
	s_addc_u32 s9, s7, 0
	v_mov_b32_e32 v1, 0
	v_mov_b32_e32 v2, 1
	s_mov_b32 s10, 0
	s_waitcnt vmcnt(0) lgkmcnt(0)
	global_atomic_add v19, v1, v2, s[8:9] sc0
.Lp0bar_cnt:
	global_load_dword v20, v1, s[6:7] sc1
	global_load_dword v3, v1, s[2:3] offset:0 sc1
	global_load_dword v4, v1, s[2:3] offset:256 sc1
	global_load_dword v5, v1, s[2:3] offset:512 sc1
	global_load_dword v6, v1, s[2:3] offset:768 sc1
	global_load_dword v7, v1, s[2:3] offset:1024 sc1
	global_load_dword v8, v1, s[2:3] offset:1280 sc1
	global_load_dword v9, v1, s[2:3] offset:1536 sc1
	global_load_dword v10, v1, s[2:3] offset:1792 sc1
	global_load_dword v11, v1, s[2:3] offset:2048 sc1
	global_load_dword v12, v1, s[2:3] offset:2304 sc1
	global_load_dword v13, v1, s[2:3] offset:2560 sc1
	global_load_dword v14, v1, s[2:3] offset:2816 sc1
	global_load_dword v15, v1, s[2:3] offset:3072 sc1
	global_load_dword v16, v1, s[2:3] offset:3328 sc1
	global_load_dword v17, v1, s[2:3] offset:3584 sc1
	global_load_dword v18, v1, s[2:3] offset:3840 sc1
	v_mov_b32_e32 v21, 0
	v_mov_b32_e32 v22, 0
	s_waitcnt vmcnt(0)
	v_add_u32_e32 v21, v21, v3
	v_min_u32_e32 v3, 1, v3
	v_add_u32_e32 v22, v22, v3
	v_add_u32_e32 v21, v21, v4
	v_min_u32_e32 v4, 1, v4
	v_add_u32_e32 v22, v22, v4
	v_add_u32_e32 v21, v21, v5
	v_min_u32_e32 v5, 1, v5
	v_add_u32_e32 v22, v22, v5
	v_add_u32_e32 v21, v21, v6
	v_min_u32_e32 v6, 1, v6
	v_add_u32_e32 v22, v22, v6
	v_add_u32_e32 v21, v21, v7
	v_min_u32_e32 v7, 1, v7
	v_add_u32_e32 v22, v22, v7
	v_add_u32_e32 v21, v21, v8
	v_min_u32_e32 v8, 1, v8
	v_add_u32_e32 v22, v22, v8
	v_add_u32_e32 v21, v21, v9
	v_min_u32_e32 v9, 1, v9
	v_add_u32_e32 v22, v22, v9
	v_add_u32_e32 v21, v21, v10
	v_min_u32_e32 v10, 1, v10
	v_add_u32_e32 v22, v22, v10
	v_add_u32_e32 v21, v21, v11
	v_min_u32_e32 v11, 1, v11
	v_add_u32_e32 v22, v22, v11
	v_add_u32_e32 v21, v21, v12
	v_min_u32_e32 v12, 1, v12
	v_add_u32_e32 v22, v22, v12
	v_add_u32_e32 v21, v21, v13
	v_min_u32_e32 v13, 1, v13
	v_add_u32_e32 v22, v22, v13
	v_add_u32_e32 v21, v21, v14
	v_min_u32_e32 v14, 1, v14
	v_add_u32_e32 v22, v22, v14
	v_add_u32_e32 v21, v21, v15
	v_min_u32_e32 v15, 1, v15
	v_add_u32_e32 v22, v22, v15
	v_add_u32_e32 v21, v21, v16
	v_min_u32_e32 v16, 1, v16
	v_add_u32_e32 v22, v22, v16
	v_add_u32_e32 v21, v21, v17
	v_min_u32_e32 v17, 1, v17
	v_add_u32_e32 v22, v22, v17
	v_add_u32_e32 v21, v21, v18
	v_min_u32_e32 v18, 1, v18
	v_add_u32_e32 v22, v22, v18
	v_cmp_eq_u32_e32 vcc, s80, v21
	s_cbranch_vccnz .Lp0bar_have
	s_sleep 1
	s_add_i32 s10, s10, 1
	s_cmp_lt_u32 s10, 0x200000
	s_cbranch_scc1 .Lp0bar_cnt
.Lp0bar_have:
	v_add_u32_e32 v19, 1, v19
	v_cmp_ne_u32_e32 vcc, v19, v20
	s_add_u32 s2, s62, 0x7400
	s_addc_u32 s3, s63, 0
	s_cbranch_vccnz .Lp0bar_member
	buffer_wbl2 sc1
	buffer_inv sc1
	s_waitcnt vmcnt(0)
	global_atomic_add v1, v2, s[2:3]
	s_branch .Lp0bar_spin

; #define VM_WAIT() asm volatile("s_waitcnt vmcnt(0)" ::: "memory")
; __device__ __forceinline__ unsigned xb_ld(unsigned* p)              { return __hip_atomic_load(p, __ATOMIC_RELAXED, __HIP_MEMORY_SCOPE_AGENT); }
; #define XB_SPIN(cond, bar) do { unsigned _sp = 0; while (cond) { __builtin_amdgcn_s_sleep(1); \
;     if ((++_sp & 255u) == 0u) { if (xb_ld(&(bar)[XB_TMO])) break; if (_sp > XB_SPIN_CAP) { atomicAdd(&(bar)[XB_TMO], 1u); break; } } } } while (0)
; __device__ __forceinline__ void xcd_barrier(const XcdBarrier& b) {
;     ...
;             else XB_SPIN(xb_ld(&bar[XB_TOPGEN]) == tg, bar);
; __device__ __forceinline__ void fcumsum(Frame& F) {
;     const int gw = F.vcu * NWAVES + F.wave;
;     if (gw >= BATCH * NH) return;
;     const int b = gw >> 3, h = gw & 7;
;     const float* src = F.logf + ((size_t)b * SEQ + 32 * F.lane) * 8 + h;
; __global__ void __launch_bounds__(NTHREADS, 2) skel_fwd(Args args) {
;     ...
;     if (IN(1)) {
;         fcumsum(F); VM_WAIT();
;     ...
;         { if (F.tid == 0) { const unsigned long long t0 = __builtin_amdgcn_s_memrealtime(), dl = (unsigned long long)(((int)blockIdx.x >> 3) & 3) * STAGGER_P1; while (__builtin_amdgcn_s_memrealtime() - t0 < dl) __builtin_amdgcn_s_sleep(8); }
;           __syncthreads(); }
;     ...
;         { pg8::EpiProj E{F.SBQ, F.G0, F.G2, F.MKf, F.MV};
;           pg8::SchedP1 S{F.G, (int)blockIdx.x, (const char*)F.XN, (const char*)F.Win_t};
;           pg8::gemm_phase<pg8::EpiProj, pg8::SchedP1, false, true, 1, DE_P1>(F.lds, D, S, E);
.Lp0bar_spin:
	global_load_dword v3, v1, s[2:3] sc1
	s_waitcnt vmcnt(0)
	v_cmp_ge_u32_e32 vcc, v3, v22
	s_cbranch_vccnz .Lp0bar_done
	s_sleep 1
	s_add_i32 s10, s10, 1
	s_cmp_lt_u32 s10, 0x200000
	s_cbranch_scc1 .Lp0bar_spin
.Lp0bar_done:
.LBB0_154:
	s_or_b64 exec, exec, s[0:1]
	s_waitcnt lgkmcnt(0)
	s_barrier
.LBB0_155:
	s_add_u32 s0, s62, 0x2c00000
	s_addc_u32 s1, s63, 0
	s_add_u32 s47, s62, 0xc000000
	v_writelane_b32 v247, s0, 49
	s_addc_u32 s84, s63, 0
	s_nop 0
	v_writelane_b32 v247, s1, 50
	s_add_u32 s0, s62, 0x180000
	v_writelane_b32 v247, s0, 51
	s_addc_u32 s0, s63, 0
	v_writelane_b32 v247, s0, 52
	s_add_u32 s0, s62, 0xe000000
	s_addc_u32 s1, s63, 0
	v_writelane_b32 v247, s0, 53
	s_nop 1
	v_writelane_b32 v247, s1, 54
	s_add_u32 s0, s62, 0x2700000
	s_addc_u32 s1, s63, 0
	v_writelane_b32 v247, s0, 55
	s_add_u32 s82, s62, 0x5000000
	s_addc_u32 s83, s63, 0
	v_writelane_b32 v247, s1, 56
	v_writelane_b32 v247, s56, 57
	s_cmp_lt_i32 s18, 2
	s_cselect_b64 s[0:1], -1, 0
	v_writelane_b32 v247, s57, 58
	s_cmp_gt_i32 s19, 1
	v_writelane_b32 v247, s58, 59
	s_cselect_b64 s[2:3], -1, 0
	v_writelane_b32 v247, s59, 60
	s_and_b64 s[0:1], s[0:1], s[2:3]
	v_writelane_b32 v247, s60, 61
	s_andn2_b64 vcc, exec, s[0:1]
	v_writelane_b32 v247, s61, 62
	v_writelane_b32 v247, s62, 63
	v_writelane_b32 v246, s63, 0
	s_cbranch_vccnz .LBB0_375
	s_lshl_b32 s0, s89, 3
	s_add_i32 s0, s0, s81
	s_cmp_gt_i32 s0, 63
	s_cbranch_scc1 .LBB0_158
; __device__ __forceinline__ void fcumsum(Frame& F) {
;     const int gw = F.vcu * NWAVES + F.wave;
;     if (gw >= BATCH * NH) return;
;     const int b = gw >> 3, h = gw & 7;
;     const float* src = F.logf + ((size_t)b * SEQ + 32 * F.lane) * 8 + h;
;     float v[32], tot = 0.f;
; #pragma unroll
;     for (int i = 0; i < 32; ++i) v[i] = src[i * 8];
; #pragma unroll
;     for (int i = 0; i < 32; ++i) tot += v[i];
;     float incl = tot;
; #pragma unroll
;     for (int off = 1; off < 64; off <<= 1) { const float y = __shfl_up(incl, off); if (F.lane >= off) incl += y; }
;     float run = incl - tot;
;     float* dst = F.FC + (size_t)gw * SEQ + 32 * F.lane;
; #pragma unroll
;     for (int i = 0; i < 32; i += 4) { f32x4 o; run += v[i]; o.x = run; run += v[i + 1]; o.y = run; run += v[i + 2]; o.z = run; run += v[i + 3]; o.w = run; *(f32x4*)(dst + i) = o; }
; }
	s_ashr_i32 s2, s0, 3
	s_ashr_i32 s3, s2, 31
	s_lshl_b64 s[2:3], s[2:3], 16
	s_add_u32 s2, s62, s2
	s_addc_u32 s3, s63, s3
	v_lshlrev_b32_e32 v2, 10, v178
	v_mov_b32_e32 v3, 0
	s_lshr_b32 s1, s88, 4
	s_mov_b32 s5, 0
	v_lshl_add_u64 v[2:3], s[2:3], 0, v[2:3]
	s_and_b32 s4, s1, 28
	v_lshl_add_u64 v[2:3], v[2:3], 0, s[4:5]
	s_mov_b64 s[2:3], 0x100000
	s_mov_b32 s1, 0x100000
	v_lshl_add_u64 v[4:5], v[2:3], 0, s[2:3]
	v_add_co_u32_e32 v2, vcc, s1, v2
	s_ashr_i32 s1, s0, 31
	s_nop 0
	v_addc_co_u32_e32 v3, vcc, 0, v3, vcc
	global_load_dword v1, v[2:3], off
	s_nop 0
	global_load_dword v3, v[4:5], off offset:32
	global_load_dword v6, v[4:5], off offset:64
	global_load_dword v7, v[4:5], off offset:96
	global_load_dword v8, v[4:5], off offset:128
	global_load_dword v9, v[4:5], off offset:160
	global_load_dword v10, v[4:5], off offset:192
	global_load_dword v11, v[4:5], off offset:224
	global_load_dword v12, v[4:5], off offset:256
	global_load_dword v13, v[4:5], off offset:288
	global_load_dword v14, v[4:5], off offset:320
	global_load_dword v15, v[4:5], off offset:352
	global_load_dword v16, v[4:5], off offset:384
	global_load_dword v17, v[4:5], off offset:416
	global_load_dword v18, v[4:5], off offset:448
	global_load_dword v19, v[4:5], off offset:480
	global_load_dword v20, v[4:5], off offset:512
	global_load_dword v21, v[4:5], off offset:544
	global_load_dword v22, v[4:5], off offset:576
	global_load_dword v23, v[4:5], off offset:608
	global_load_dword v24, v[4:5], off offset:640
	global_load_dword v25, v[4:5], off offset:672
	global_load_dword v26, v[4:5], off offset:704
	global_load_dword v27, v[4:5], off offset:736
	global_load_dword v28, v[4:5], off offset:768
	global_load_dword v29, v[4:5], off offset:800
	global_load_dword v30, v[4:5], off offset:832
	global_load_dword v31, v[4:5], off offset:864
	global_load_dword v32, v[4:5], off offset:896
	global_load_dword v33, v[4:5], off offset:928
	global_load_dword v34, v[4:5], off offset:960
	global_load_dword v35, v[4:5], off offset:992
	v_mbcnt_lo_u32_b32 v2, -1, 0
	v_mbcnt_hi_u32_b32 v2, -1, v2
	v_and_b32_e32 v4, 64, v2
	v_add_u32_e32 v5, -1, v2
	v_cmp_lt_i32_e32 vcc, v5, v4
	v_add_u32_e32 v38, -2, v2
	v_add_u32_e32 v39, -4, v2
	v_cndmask_b32_e32 v5, v5, v2, vcc
	v_lshlrev_b32_e32 v5, 2, v5
	v_cmp_lt_i32_e32 vcc, v38, v4
	s_lshl_b64 s[0:1], s[0:1], 13
	v_readlane_b32 s2, v247, 51
	v_cndmask_b32_e32 v38, v38, v2, vcc
	v_cmp_eq_u32_e32 vcc, 0, v178
	v_lshlrev_b32_e32 v38, 2, v38
	s_add_u32 s0, s2, s0
	v_readlane_b32 s2, v247, 52
	v_lshlrev_b32_e32 v36, 7, v178
	s_addc_u32 s1, s2, s1
	s_waitcnt vmcnt(31)
	v_add_f32_e32 v37, 0, v1
	s_waitcnt vmcnt(30)
	v_add_f32_e32 v37, v37, v3
	s_waitcnt vmcnt(29)
	v_add_f32_e32 v37, v37, v6
	s_waitcnt vmcnt(28)
	v_add_f32_e32 v37, v37, v7
	s_waitcnt vmcnt(27)
	v_add_f32_e32 v37, v37, v8
	s_waitcnt vmcnt(26)
	v_add_f32_e32 v37, v37, v9
	s_waitcnt vmcnt(25)
	v_add_f32_e32 v37, v37, v10
	s_waitcnt vmcnt(24)
	v_add_f32_e32 v37, v37, v11
	s_waitcnt vmcnt(23)
	v_add_f32_e32 v37, v37, v12
	s_waitcnt vmcnt(22)
	v_add_f32_e32 v37, v37, v13
	s_waitcnt vmcnt(21)
	v_add_f32_e32 v37, v37, v14
	s_waitcnt vmcnt(20)
	v_add_f32_e32 v37, v37, v15
	s_waitcnt vmcnt(19)
	v_add_f32_e32 v37, v37, v16
	s_waitcnt vmcnt(18)
	v_add_f32_e32 v37, v37, v17
	s_waitcnt vmcnt(17)
	v_add_f32_e32 v37, v37, v18
	s_waitcnt vmcnt(16)
	v_add_f32_e32 v37, v37, v19
	s_waitcnt vmcnt(15)
	v_add_f32_e32 v37, v37, v20
	s_waitcnt vmcnt(14)
	v_add_f32_e32 v37, v37, v21
	s_waitcnt vmcnt(13)
	v_add_f32_e32 v37, v37, v22
	s_waitcnt vmcnt(12)
	v_add_f32_e32 v37, v37, v23
	s_waitcnt vmcnt(11)
	v_add_f32_e32 v37, v37, v24
	s_waitcnt vmcnt(10)
	v_add_f32_e32 v37, v37, v25
	s_waitcnt vmcnt(9)
	v_add_f32_e32 v37, v37, v26
	s_waitcnt vmcnt(8)
	v_add_f32_e32 v37, v37, v27
	s_waitcnt vmcnt(7)
	v_add_f32_e32 v37, v37, v28
	s_waitcnt vmcnt(6)
	v_add_f32_e32 v37, v37, v29
	s_waitcnt vmcnt(5)
	v_add_f32_e32 v37, v37, v30
	s_waitcnt vmcnt(4)
	v_add_f32_e32 v37, v37, v31
	s_waitcnt vmcnt(3)
	v_add_f32_e32 v37, v37, v32
	s_waitcnt vmcnt(2)
	v_add_f32_e32 v37, v37, v33
	s_waitcnt vmcnt(1)
	v_add_f32_e32 v37, v37, v34
	s_waitcnt vmcnt(0)
	v_add_f32_e32 v37, v37, v35
	ds_bpermute_b32 v5, v5, v37
	s_waitcnt lgkmcnt(0)
	v_add_f32_e32 v5, v37, v5
	v_cndmask_b32_e32 v5, v5, v37, vcc
	ds_bpermute_b32 v38, v38, v5
	v_cmp_lt_i32_e32 vcc, v39, v4
	s_waitcnt lgkmcnt(0)
	v_add_f32_e32 v38, v5, v38
	v_cndmask_b32_e32 v39, v39, v2, vcc
	v_cmp_gt_u32_e32 vcc, 2, v178
	v_lshlrev_b32_e32 v39, 2, v39
	s_nop 0
	v_cndmask_b32_e32 v5, v38, v5, vcc
	ds_bpermute_b32 v38, v39, v5
	v_add_u32_e32 v39, -8, v2
	v_cmp_lt_i32_e32 vcc, v39, v4
	s_waitcnt lgkmcnt(0)
	v_add_f32_e32 v38, v5, v38
	v_cndmask_b32_e32 v39, v39, v2, vcc
	v_cmp_gt_u32_e32 vcc, 4, v178
	v_lshlrev_b32_e32 v39, 2, v39
	s_nop 0
	v_cndmask_b32_e32 v5, v38, v5, vcc
	ds_bpermute_b32 v38, v39, v5
	v_add_u32_e32 v39, -16, v2
	v_cmp_lt_i32_e32 vcc, v39, v4
	s_waitcnt lgkmcnt(0)
	v_add_f32_e32 v38, v5, v38
	v_cndmask_b32_e32 v39, v39, v2, vcc
	v_cmp_gt_u32_e32 vcc, 8, v178
	v_lshlrev_b32_e32 v39, 2, v39
	s_nop 0
	v_cndmask_b32_e32 v5, v38, v5, vcc
	ds_bpermute_b32 v38, v39, v5
	v_subrev_u32_e32 v39, 32, v2
	v_cmp_lt_i32_e32 vcc, v39, v4
	s_waitcnt lgkmcnt(0)
	v_add_f32_e32 v4, v5, v38
	v_cndmask_b32_e32 v2, v39, v2, vcc
	v_cmp_gt_u32_e32 vcc, 16, v178
	v_lshlrev_b32_e32 v2, 2, v2
	s_nop 0
	v_cndmask_b32_e32 v4, v4, v5, vcc
	ds_bpermute_b32 v2, v2, v4
	v_cmp_gt_u32_e32 vcc, 32, v178
	s_waitcnt lgkmcnt(0)
	v_add_f32_e32 v2, v4, v2
	v_cndmask_b32_e32 v2, v2, v4, vcc
	v_sub_f32_e32 v2, v2, v37
	v_add_f32_e32 v2, v1, v2
	v_add_f32_e32 v3, v3, v2
	v_add_f32_e32 v4, v6, v3
	v_add_f32_e32 v5, v7, v4
	global_store_dwordx4 v36, v[2:5], s[0:1]
	s_nop 1
	v_add_f32_e32 v2, v8, v5
	v_add_f32_e32 v3, v9, v2
	v_add_f32_e32 v4, v10, v3
	v_add_f32_e32 v5, v11, v4
	global_store_dwordx4 v36, v[2:5], s[0:1] offset:16
	s_nop 1
	v_add_f32_e32 v2, v12, v5
	v_add_f32_e32 v3, v13, v2
	v_add_f32_e32 v4, v14, v3
	v_add_f32_e32 v5, v15, v4
	global_store_dwordx4 v36, v[2:5], s[0:1] offset:32
	s_nop 1
	v_add_f32_e32 v2, v16, v5
	v_add_f32_e32 v3, v17, v2
	v_add_f32_e32 v4, v18, v3
	v_add_f32_e32 v5, v19, v4
	global_store_dwordx4 v36, v[2:5], s[0:1] offset:48
	s_nop 1
	v_add_f32_e32 v2, v20, v5
	v_add_f32_e32 v3, v21, v2
	v_add_f32_e32 v4, v22, v3
	v_add_f32_e32 v5, v23, v4
	global_store_dwordx4 v36, v[2:5], s[0:1] offset:64
	s_nop 1
	v_add_f32_e32 v2, v24, v5
	v_add_f32_e32 v3, v25, v2
	v_add_f32_e32 v4, v26, v3
	v_add_f32_e32 v5, v27, v4
	global_store_dwordx4 v36, v[2:5], s[0:1] offset:80
	s_nop 1
	v_add_f32_e32 v2, v28, v5
	v_add_f32_e32 v3, v29, v2
	v_add_f32_e32 v4, v30, v3
	v_add_f32_e32 v5, v31, v4
	global_store_dwordx4 v36, v[2:5], s[0:1] offset:96
	s_nop 1
	v_add_f32_e32 v2, v32, v5
	v_add_f32_e32 v3, v33, v2
	v_add_f32_e32 v4, v34, v3
	v_add_f32_e32 v5, v35, v4
	global_store_dwordx4 v36, v[2:5], s[0:1] offset:112
